# hgrn local: storing waves request the next item's rows before their 16 KiB result stores (counted wait leaves the stores in flight)
# baseline (speedup 1.0000x reference)
; #define LAS __attribute__((address_space(3)))
; #define REPS(bit) for (int rep_ = 0; rep_ < 1 + ((MK_REP >> (bit)) & 1); ++rep_)
; template <bool OUT> __device__ __forceinline__ void hgrn_pair(const PA& a, LAS unsigned char* lds, int layer, int bh, int s, int wave, int lane) {
;     const int half = wave >> 2, wl = wave & 3, c = half ? 63 - s : s, b = bh >> 2, h = bh & 3, item = bh * 64 + c;
;     float* HU = (float*)(a.ws + WS_HU); float* HA = (float*)(a.ws + WS_HA);
;     LAS unsigned char* wb = lds + wave * 12800;
;     LAS float* DLs = (LAS float*)(wb + 11520);
;     LAS float* SBUF = (LAS float*)(lds + 102400 + half * 16384);
;     LAS float* DALL = (LAS float*)(lds + 135168 + half * 2048);
;     int l15 = lane & 15, q = lane >> 4;
;     const size_t rowc0 = (size_t)b * T + (size_t)c * 128 + (size_t)(2 * wl) * 16;
; __global__ void __launch_bounds__(NWAVES * 64, 2) hymba_fwd(Args args) {
;     ...
;             if (EN(3)) REPS(3) for (int v = vcu; v < 256; v += G) hgrn_pair<false>(pa, lds, layer, v >> 5, v & 31, wave, lane);
.Lmy_lb_done:
	s_mov_b32 s99, 0
	v_readlane_b32 s30, v252, 0
	s_cmpk_lg_i32 s92, 0x100
	s_cbranch_scc1 .LBB0_460
	s_bitcmp0_b32 s30, 4
	s_cbranch_scc1 .LBB0_502
	s_addk_i32 s30, 0xfff0
	s_branch .LBB0_460

; #define LAS __attribute__((address_space(3)))
; template <bool OUT> __device__ __forceinline__ HRaw hgrn_loadc(const PA& a, int bh, int c, int chunk, int lane) {
;     const bf16* pr = (const bf16*)(a.ws + WS_PROJ) + ((size_t)(bh >> 2) * T + (size_t)c * 128 + chunk * 16 + (lane >> 3)) * DIN + (bh & 3) * 64 + (lane & 7) * 8;
;     HRaw r;
; #pragma unroll
;     for (int k = 0; k < 2; ++k) { r.f[k] = *(const v4u*)(pr + (size_t)(8 * k) * DIN + 256); r.v[k] = *(const v4u*)(pr + (size_t)(8 * k) * DIN + 512);
;         if (OUT) { r.q[k] = *(const v4u*)(pr + (size_t)(8 * k) * DIN); } }
; template <bool OUT> __device__ __forceinline__ void hgrn_chunk(const PA& a, LAS unsigned char* wb, LAS float* DLk, LAS float* E7k, LAS float* DALLk, int layer, int h, int lane, const HRaw& raw, ...
;     ...
;         const int rr = lane >> 3, cc = (lane & 7) * 8;
; #pragma unroll
;         for (int k = 0; k < 2; ++k) { *(LAS v4u*)(RF + (rr + 8 * k) * 72 + cc) = raw.f[k]; *(LAS v4u*)(RV + (rr + 8 * k) * 72 + cc) = raw.v[k]; if (OUT) *(LAS v4u*)(RQ + (rr + 8 * k) * 72 + cc) = raw.q[k]; }
; template <bool OUT> __device__ __forceinline__ void hgrn_pair(const PA& a, LAS unsigned char* lds, int layer, int bh, int s, int wave, int lane) {
;     const int half = wave >> 2, wl = wave & 3, c = half ? 63 - s : s, b = bh >> 2, h = bh & 3, item = bh * 64 + c;
;     float* HU = (float*)(a.ws + WS_HU); float* HA = (float*)(a.ws + WS_HA);
;     LAS unsigned char* wb = lds + wave * 12800;
;     LAS float* DLs = (LAS float*)(wb + 11520);
;     LAS float* SBUF = (LAS float*)(lds + 102400 + half * 16384);
;     LAS float* DALL = (LAS float*)(lds + 135168 + half * 2048);
;     int l15 = lane & 15, q = lane >> 4;
;     const size_t rowc0 = (size_t)b * T + (size_t)c * 128 + (size_t)(2 * wl) * 16;
;     __syncthreads();
;     f32x4 U0[4][4], Up[4][4], o[2][4]; bf16x8 qf[2][2];
;     { const HRaw r0 = hgrn_loadc<OUT>(a, bh, c, 2 * wl, lane); hgrn_chunk<OUT>(a, wb, DLs, DLs + 128, DALL + (2 * wl) * 64, layer, h, lane, r0, U0, o[0], qf[0]); }
.LBB0_460:
	s_and_b32 s3, s30, 31
	s_ashr_i32 s2, s30, 5
	s_xor_b32 s24, s3, 63
	s_and_b64 s[0:1], s[10:11], exec
	s_cselect_b32 s31, s3, s24
	s_ashr_i32 s0, s30, 7
	s_ashr_i32 s1, s0, 31
	s_lshl_b64 s[24:25], s[0:1], 13
	s_lshl_b32 s0, s31, 7
	s_or_b32 s24, s24, s0
	v_or_b32_e32 v2, s24, v142
	v_mov_b64_e32 v[0:1], s[60:61]
	s_lshl_b32 s37, s2, 6
	v_mad_u64_u32 v[0:1], s[0:1], v2, s93, v[0:1]
	v_mov_b32_e32 v2, 0x1c00
	s_and_b32 s0, s37, 0xc0
	v_mad_i32_i24 v1, s25, v2, v1
	s_lshl_b32 s62, s0, 1
	v_lshl_add_u64 v[0:1], v[0:1], 0, s[62:63]
	v_lshl_add_u64 v[8:9], v[0:1], 0, v[220:221]
	v_add_co_u32_e32 v12, vcc, s55, v8
	s_nop 1
	v_addc_co_u32_e32 v13, vcc, 0, v9, vcc
	s_barrier
	s_cmp_eq_u32 s99, 0
	s_cbranch_scc1 .Lmy_hlp_norm
	s_mov_b32 s99, 0
	s_waitcnt vmcnt(21) lgkmcnt(0)
	ds_write_b128 v143, v[184:187]
	ds_write_b128 v143, v[188:191] offset:2304
	ds_write_b128 v143, v[192:195] offset:1152
	ds_write_b128 v143, v[196:199] offset:3456
	s_waitcnt lgkmcnt(0)
	s_and_b32 s38, s2, 3
	s_andn2_b64 vcc, exec, s[4:5]
	s_branch .Lmy_hlp_join
.Lmy_hlp_norm:
	global_load_dwordx4 v[0:3], v[8:9], off offset:512
	global_load_dwordx4 v[4:7], v[8:9], off offset:1024
	s_nop 0
	global_load_dwordx4 v[8:11], v[12:13], off offset:512
	s_nop 0
	global_load_dwordx4 v[12:15], v[12:13], off offset:1024
	v_ashrrev_i32_e32 v180, 3, v140
	v_mov_b32_e32 v181, s24
	v_or_b32_e32 v181, s12, v181
	v_add_u32_e32 v180, v181, v180
	v_mul_lo_u32 v180, v180, s93
	v_and_b32_e32 v181, 7, v140
	v_lshlrev_b32_e32 v181, 4, v181
	v_add3_u32 v180, v180, v181, s62
	global_load_dwordx4 v[160:163], v180, s[60:61] offset:512
	global_load_dwordx4 v[164:167], v180, s[60:61] offset:1024
	v_add_u32_e32 v181, s55, v180
	global_load_dwordx4 v[168:171], v181, s[60:61] offset:512
	global_load_dwordx4 v[172:175], v181, s[60:61] offset:1024
	s_waitcnt lgkmcnt(0)
	s_and_b32 s38, s2, 3
	s_andn2_b64 vcc, exec, s[4:5]
	s_waitcnt vmcnt(7)
	ds_write_b128 v143, v[0:3]
	s_waitcnt vmcnt(6)
	ds_write_b128 v143, v[4:7] offset:2304
	s_waitcnt vmcnt(5)
	ds_write_b128 v143, v[8:11] offset:1152
	s_waitcnt vmcnt(4)
	ds_write_b128 v143, v[12:15] offset:3456
.Lmy_hlp_join:
	s_waitcnt lgkmcnt(0)
	v_cndmask_b32_e64 v1, 0, 1, s[4:5]
	v_mov_b32_e32 v0, 0
	v_cmp_ne_u32_e64 s[0:1], 1, v1
	v_mov_b32_e32 v1, 0
	s_cbranch_vccnz .LBB0_462
	v_mov_b32_e32 v1, v176

; template <bool OUT> __device__ __forceinline__ HRaw hgrn_loadc(const PA& a, int bh, int c, int chunk, int lane) {
;     const bf16* pr = (const bf16*)(a.ws + WS_PROJ) + ((size_t)(bh >> 2) * T + (size_t)c * 128 + chunk * 16 + (lane >> 3)) * DIN + (bh & 3) * 64 + (lane & 7) * 8;
;     HRaw r;
; #pragma unroll
;     for (int k = 0; k < 2; ++k) { r.f[k] = *(const v4u*)(pr + (size_t)(8 * k) * DIN + 256); r.v[k] = *(const v4u*)(pr + (size_t)(8 * k) * DIN + 512);
;         if (OUT) { r.q[k] = *(const v4u*)(pr + (size_t)(8 * k) * DIN); } }
; template <bool OUT> __device__ __forceinline__ void hgrn_pair(const PA& a, LAS unsigned char* lds, int layer, int bh, int s, int wave, int lane) {
;     ...
;         if (wl == 3) {
; #pragma unroll
;             for (int mt = 0; mt < 4; ++mt)
; #pragma unroll
;                 for (int nt = 0; nt < 4; ++nt)
;                     *(f32x4*)(HU + (size_t)item * 4096 + (size_t)((mt * 4 + nt) * 64 + lane) * 4) = Up[mt][nt];
;             float sm = 0.f;
; #pragma unroll
;             for (int w2 = 0; w2 < 8; ++w2) sm += DALL[w2 * 64 + lane];
;             HA[(size_t)item * 64 + lane] = __expf(sm);
;         }
.LBB0_500:
	s_andn2_b64 vcc, exec, s[20:21]
	s_cbranch_vccnz .LBB0_459
	s_cmpk_lg_i32 s92, 0x100
	s_cbranch_scc1 .Lmy_hlp_nopf
	s_bitcmp1_b32 s30, 4
	s_cbranch_scc1 .Lmy_hlp_nopf
	s_add_i32 s98, s30, 16
	s_and_b32 s99, s98, 31
	s_ashr_i32 s2, s98, 5
	s_xor_b32 s24, s99, 63
	s_and_b64 s[0:1], s[10:11], exec
	s_cselect_b32 s99, s99, s24
	s_ashr_i32 s0, s98, 7
	s_ashr_i32 s1, s0, 31
	s_lshl_b64 s[24:25], s[0:1], 13
	s_lshl_b32 s0, s99, 7
	s_or_b32 s24, s24, s0
	v_or_b32_e32 v202, s24, v142
	v_mov_b64_e32 v[200:201], s[60:61]
	s_lshl_b32 s3, s2, 6
	v_mad_u64_u32 v[200:201], vcc, v202, s93, v[200:201]
	v_mov_b32_e32 v203, 0x1c00
	s_and_b32 s0, s3, 0xc0
	v_mad_i32_i24 v201, s25, v203, v201
	s_lshl_b32 s0, s0, 1
	s_mov_b32 s1, 0
	v_lshl_add_u64 v[200:201], v[200:201], 0, s[0:1]
	v_lshl_add_u64 v[204:205], v[200:201], 0, v[220:221]
	v_add_co_u32_e32 v206, vcc, s55, v204
	s_nop 1
	v_addc_co_u32_e32 v207, vcc, 0, v205, vcc
	global_load_dwordx4 v[184:187], v[204:205], off offset:512
	global_load_dwordx4 v[188:191], v[204:205], off offset:1024
	global_load_dwordx4 v[192:195], v[206:207], off offset:512
	global_load_dwordx4 v[196:199], v[206:207], off offset:1024
	v_ashrrev_i32_e32 v208, 3, v140
	v_mov_b32_e32 v209, s24
	v_or_b32_e32 v209, s12, v209
	v_add_u32_e32 v208, v209, v208
	v_mul_lo_u32 v208, v208, s93
	v_and_b32_e32 v209, 7, v140
	v_lshlrev_b32_e32 v209, 4, v209
	v_add3_u32 v208, v208, v209, s0
	global_load_dwordx4 v[160:163], v208, s[60:61] offset:512
	global_load_dwordx4 v[164:167], v208, s[60:61] offset:1024
	v_add_u32_e32 v209, s55, v208
	global_load_dwordx4 v[168:171], v209, s[60:61] offset:512
	global_load_dwordx4 v[172:175], v209, s[60:61] offset:1024
	s_mov_b32 s99, 1
.Lmy_hlp_nopf:
	s_or_b32 s0, s31, s37
	s_ashr_i32 s1, s0, 31
	s_lshl_b64 s[2:3], s[0:1], 14
	s_add_u32 s2, s89, s2
	v_readlane_b32 s24, v253, 9
	s_addc_u32 s3, s24, s3
	v_ashrrev_i32_e32 v145, 31, v144
	v_lshl_add_u64 v[64:65], v[144:145], 4, s[2:3]
	global_store_dwordx4 v[64:65], v[60:63], off
	s_lshl_b64 s[0:1], s[0:1], 8
	s_add_u32 s0, s39, s0
	v_add_u32_e32 v60, 64, v144
	v_ashrrev_i32_e32 v61, 31, v60
	v_lshl_add_u64 v[60:61], v[60:61], 4, s[2:3]
	global_store_dwordx4 v[60:61], v[56:59], off
	s_addc_u32 s1, s54, s1
	s_nop 0
	v_add_u32_e32 v56, 0x80, v144
	v_ashrrev_i32_e32 v57, 31, v56
	v_lshl_add_u64 v[56:57], v[56:57], 4, s[2:3]
	global_store_dwordx4 v[56:57], v[52:55], off
	s_nop 1
	v_add_u32_e32 v52, 0xc0, v144
	v_ashrrev_i32_e32 v53, 31, v52
	v_lshl_add_u64 v[52:53], v[52:53], 4, s[2:3]
	global_store_dwordx4 v[52:53], v[48:51], off
	s_nop 1
	v_add_u32_e32 v48, 0x100, v144
	v_ashrrev_i32_e32 v49, 31, v48
	v_lshl_add_u64 v[48:49], v[48:49], 4, s[2:3]
	global_store_dwordx4 v[48:49], v[44:47], off
	s_nop 1
	v_add_u32_e32 v44, 0x140, v144
	v_ashrrev_i32_e32 v45, 31, v44
	v_lshl_add_u64 v[44:45], v[44:45], 4, s[2:3]
	global_store_dwordx4 v[44:45], v[40:43], off
	s_nop 1
	v_add_u32_e32 v40, 0x180, v144
	v_ashrrev_i32_e32 v41, 31, v40
	v_lshl_add_u64 v[40:41], v[40:41], 4, s[2:3]
	global_store_dwordx4 v[40:41], v[36:39], off
	s_nop 1
	v_add_u32_e32 v36, 0x1c0, v144
	v_ashrrev_i32_e32 v37, 31, v36
	v_lshl_add_u64 v[36:37], v[36:37], 4, s[2:3]
	global_store_dwordx4 v[36:37], v[32:35], off
	s_nop 1
	v_add_u32_e32 v32, 0x200, v144
	v_ashrrev_i32_e32 v33, 31, v32
	v_lshl_add_u64 v[32:33], v[32:33], 4, s[2:3]
	global_store_dwordx4 v[32:33], v[28:31], off
	s_nop 1
	v_add_u32_e32 v28, 0x240, v144
	v_ashrrev_i32_e32 v29, 31, v28
	v_lshl_add_u64 v[28:29], v[28:29], 4, s[2:3]
	global_store_dwordx4 v[28:29], v[24:27], off
	s_nop 1
	v_add_u32_e32 v24, 0x280, v144
	v_ashrrev_i32_e32 v25, 31, v24
	v_lshl_add_u64 v[24:25], v[24:25], 4, s[2:3]
	global_store_dwordx4 v[24:25], v[20:23], off
	s_nop 1
	v_add_u32_e32 v20, 0x2c0, v144
	v_ashrrev_i32_e32 v21, 31, v20
	v_lshl_add_u64 v[20:21], v[20:21], 4, s[2:3]
	global_store_dwordx4 v[20:21], v[16:19], off
	s_nop 1
	v_add_u32_e32 v16, 0x300, v144
	v_ashrrev_i32_e32 v17, 31, v16
	v_lshl_add_u64 v[16:17], v[16:17], 4, s[2:3]
	global_store_dwordx4 v[16:17], v[12:15], off
	s_nop 1
	v_add_u32_e32 v12, 0x340, v144
	v_ashrrev_i32_e32 v13, 31, v12
	v_lshl_add_u64 v[12:13], v[12:13], 4, s[2:3]
	global_store_dwordx4 v[12:13], v[8:11], off
	s_nop 1
	v_add_u32_e32 v8, 0x380, v144
	v_ashrrev_i32_e32 v9, 31, v8
	v_lshl_add_u64 v[8:9], v[8:9], 4, s[2:3]
	global_store_dwordx4 v[8:9], v[4:7], off
	v_lshl_add_u32 v8, v144, 2, s15
	ds_read2st64_b32 v[6:7], v8 offset1:1
	v_add_u32_e32 v4, 0x3c0, v144
	v_ashrrev_i32_e32 v5, 31, v4
	v_lshl_add_u64 v[4:5], v[4:5], 4, s[2:3]
	global_store_dwordx4 v[4:5], v[0:3], off
	ds_read2st64_b32 v[0:1], v8 offset0:2 offset1:3
	ds_read2st64_b32 v[2:3], v8 offset0:4 offset1:5
	ds_read2st64_b32 v[4:5], v8 offset0:6 offset1:7
	s_waitcnt lgkmcnt(3)
	v_add_f32_e32 v6, 0, v6
	v_add_f32_e32 v6, v6, v7
	s_waitcnt lgkmcnt(2)
	v_add_f32_e32 v0, v6, v0
	v_add_f32_e32 v0, v0, v1
	s_waitcnt lgkmcnt(1)
	v_add_f32_e32 v0, v0, v2
	v_add_f32_e32 v0, v0, v3
	s_waitcnt lgkmcnt(0)
	v_add_f32_e32 v0, v0, v4
	v_add_f32_e32 v0, v0, v5
	v_mul_f32_e32 v0, 0x3fb8aa3b, v0
	v_exp_f32_e32 v2, v0
	v_lshl_add_u64 v[0:1], v[144:145], 2, s[0:1]
	global_store_dword v[0:1], v2, off
	s_branch .LBB0_459
